# G6 epilogue rewritten as 4-deep load pipeline into dead fragment regs (no per-step vmcnt(0))
# speedup vs baseline: 1.0004x; 1.0004x over previous
; DI unsigned pk2(float lo, float hi) { return pg8::cvt_pk_bf16(lo, hi); }
;     DI void operator()(const f32x4 (&acc)[2][2][4][2], const Unit& u, int wr, int wc, int fr, int fq) const {
;         const int row0 = u.pm * 256 + wr * 64 + fr, col0 = u.pn * 256 + wc * 32 + 8 * fq;
;         const int bb = (grow0 + u.pm * 256) >> 11;
;         f32x4 bs[2][2];
; #pragma unroll
;         for (int bj = 0; bj < 2; ++bj) { const float* bp = bias2 + (size_t)bb * 4096 + col0 + bj * 128; bs[bj][0] = *(const f32x4*)bp; bs[bj][1] = *(const f32x4*)(bp + 4); }
; #pragma unroll
;         for (int ai = 0; ai < 2; ++ai)
; #pragma unroll
;             for (int m = 0; m < 4; ++m) { bf16* rowp = O + (size_t)(row0 + ai * 128 + m * 16) * 4096 + col0;
;                 const float rstd = rsqrtf(rowss[row0 + ai * 128 + m * 16] * (1.0f / 1024.0f) + 1e-6f);
; #pragma unroll
;                 for (int bj = 0; bj < 2; ++bj) { f32x4 v0 = acc[ai][bj][m][0] * rstd + bs[bj][0], v1 = acc[ai][bj][m][1] * rstd + bs[bj][1];
; #pragma unroll
;                     for (int i = 0; i < 4; ++i) { float a = fmaxf(v0[i], 0.f), b = fmaxf(v1[i], 0.f); v0[i] = a * a; v1[i] = b * b; }
;                     v4u w; w.x = pk2(v0[0], v0[1]); w.y = pk2(v0[2], v0[3]); w.z = pk2(v1[0], v1[1]); w.w = pk2(v1[2], v1[3]);
;                     *(v4u*)(rowp + bj * 128) = w; } }
.LBB0_742:
	s_lshl_b32 s17, s38, 8
	v_readlane_b32 s2, v254, 56
	s_add_i32 s2, s17, s2
	v_readlane_b32 s3, v254, 57
	s_ashr_i32 s2, s2, 11
	s_ashr_i32 s3, s2, 31
	v_add_u32_e32 v160, s17, v180
	v_lshl_or_b32 v156, s37, 8, v182
	s_lshl_b64 s[2:3], s[2:3], 14
	v_readlane_b32 s24, v251, 44
	v_ashrrev_i32_e32 v161, 31, v160
	v_readlane_b32 s25, v251, 45
	s_add_u32 s2, s24, s2
	v_ashrrev_i32_e32 v157, 31, v156
	v_lshlrev_b64 v[158:159], 13, v[160:161]
	s_addc_u32 s3, s25, s3
	v_lshl_add_u64 v[158:159], s[86:87], 0, v[158:159]
	v_lshlrev_b64 v[178:179], 1, v[156:157]
	v_lshl_add_u64 v[46:47], v[156:157], 2, s[2:3]
	v_lshl_add_u64 v[156:157], v[158:159], 0, v[178:179]
	v_lshl_add_u64 v[158:159], v[160:161], 2, s[12:13]
	global_load_dwordx4 v[58:61], v[46:47], off offset:16
	global_load_dwordx4 v[62:65], v[46:47], off
	global_load_dwordx4 v[42:45], v[46:47], off offset:528
	s_nop 0
	global_load_dwordx4 v[46:49], v[46:47], off offset:512
	s_mov_b32 s17, 0x800000
	global_load_dword v161, v[158:159], off
	s_mov_b64 s[2:3], 0x100000
	s_waitcnt vmcnt(0)
	v_fmamk_f32 v161, v161, 0x3a800000, v192
	v_cmp_gt_f32_e32 vcc, s17, v161
	v_mul_f32_e32 v162, 0x4b800000, v161
	s_nop 0
	v_cndmask_b32_e32 v161, v161, v162, vcc
	v_rsq_f32_e32 v161, v161
	s_nop 0
	v_mul_f32_e32 v162, 0x45800000, v161
	v_cndmask_b32_e32 v162, v161, v162, vcc
	v_pk_fma_f32 v[138:139], v[138:139], v[162:163], v[58:59] op_sel_hi:[1,0,1]
	v_pk_fma_f32 v[142:143], v[142:143], v[162:163], v[62:63] op_sel_hi:[1,0,1]
	v_pk_fma_f32 v[140:141], v[140:141], v[162:163], v[60:61] op_sel_hi:[1,0,1]
	v_max_f32_e32 v138, 0, v138
	v_pk_fma_f32 v[144:145], v[144:145], v[162:163], v[64:65] op_sel_hi:[1,0,1]
	v_mul_f32_e32 v161, v138, v138
	v_max_f32_e32 v138, 0, v143
	v_max_f32_e32 v139, 0, v139
	v_max_f32_e32 v140, 0, v140
	v_max_f32_e32 v142, 0, v142
	v_mul_f32_e32 v138, v138, v138
	v_mul_f32_e32 v143, v139, v139
	v_max_f32_e32 v139, 0, v144
	v_mul_f32_e32 v144, v140, v140
	v_max_f32_e32 v140, 0, v145
	v_max_f32_e32 v141, 0, v141
	v_pk_fma_f32 v[132:133], v[132:133], v[162:163], v[44:45] op_sel_hi:[1,0,1]
	v_pk_fma_f32 v[130:131], v[130:131], v[162:163], v[42:43] op_sel_hi:[1,0,1]
	v_mul_f32_e32 v142, v142, v142
	v_mul_f32_e32 v139, v139, v139
	v_mul_f32_e32 v140, v140, v140
	v_mul_f32_e32 v141, v141, v141
	v_cvt_pk_bf16_f32 v138, v142, v138
	v_pk_fma_f32 v[136:137], v[136:137], v[162:163], v[48:49] op_sel_hi:[1,0,1]
	v_pk_fma_f32 v[134:135], v[134:135], v[162:163], v[46:47] op_sel_hi:[1,0,1]
	v_max_f32_e32 v130, 0, v130
	v_max_f32_e32 v131, 0, v131
	v_max_f32_e32 v132, 0, v132
	v_cvt_pk_bf16_f32 v139, v139, v140
	v_cvt_pk_bf16_f32 v140, v161, v143
	v_cvt_pk_bf16_f32 v141, v144, v141
	global_store_dwordx4 v[156:157], v[138:141], off
	v_max_f32_e32 v133, 0, v133
	v_max_f32_e32 v134, 0, v134
	v_mul_f32_e32 v138, v130, v130
	v_max_f32_e32 v130, 0, v135
	v_mul_f32_e32 v135, v131, v131
	v_max_f32_e32 v131, 0, v136
	v_mul_f32_e32 v136, v132, v132
	v_max_f32_e32 v132, 0, v137
	v_mul_f32_e32 v130, v130, v130
	v_mul_f32_e32 v131, v131, v131
	v_mul_f32_e32 v132, v132, v132
	v_mul_f32_e32 v133, v133, v133
	v_mul_f32_e32 v134, v134, v134
	v_cvt_pk_bf16_f32 v130, v134, v130
	v_cvt_pk_bf16_f32 v131, v131, v132
	v_cvt_pk_bf16_f32 v132, v138, v135
	v_cvt_pk_bf16_f32 v133, v136, v133
	global_store_dwordx4 v[156:157], v[130:133], off offset:256
	global_load_dword v132, v[158:159], off offset:64
	s_nop 0
	v_or_b32_e32 v130, 16, v160
	v_ashrrev_i32_e32 v131, 31, v130
	v_lshlrev_b64 v[130:131], 13, v[130:131]
	v_lshl_add_u64 v[130:131], s[86:87], 0, v[130:131]
	v_lshl_add_u64 v[130:131], v[130:131], 0, v[178:179]
	s_waitcnt vmcnt(0)
	v_fmamk_f32 v132, v132, 0x3a800000, v192
	v_cmp_gt_f32_e32 vcc, s17, v132
	v_mul_f32_e32 v133, 0x4b800000, v132
	s_nop 0
	v_cndmask_b32_e32 v132, v132, v133, vcc
	v_rsq_f32_e32 v132, v132
	s_nop 0
	v_mul_f32_e32 v133, 0x45800000, v132
	v_cndmask_b32_e32 v132, v132, v133, vcc
	v_pk_fma_f32 v[122:123], v[122:123], v[132:133], v[58:59] op_sel_hi:[1,0,1]
	v_pk_fma_f32 v[126:127], v[126:127], v[132:133], v[62:63] op_sel_hi:[1,0,1]
	v_pk_fma_f32 v[124:125], v[124:125], v[132:133], v[60:61] op_sel_hi:[1,0,1]
	v_max_f32_e32 v122, 0, v122
	v_pk_fma_f32 v[128:129], v[128:129], v[132:133], v[64:65] op_sel_hi:[1,0,1]
	v_mul_f32_e32 v133, v122, v122
	v_max_f32_e32 v122, 0, v127
	v_max_f32_e32 v123, 0, v123
	v_max_f32_e32 v124, 0, v124
	v_max_f32_e32 v126, 0, v126
	v_mul_f32_e32 v122, v122, v122
	v_mul_f32_e32 v127, v123, v123
	v_max_f32_e32 v123, 0, v128
	v_mul_f32_e32 v128, v124, v124
	v_max_f32_e32 v124, 0, v129
	v_max_f32_e32 v125, 0, v125
	v_pk_fma_f32 v[116:117], v[116:117], v[132:133], v[44:45] op_sel_hi:[1,0,1]
	v_pk_fma_f32 v[114:115], v[114:115], v[132:133], v[42:43] op_sel_hi:[1,0,1]
	v_mul_f32_e32 v126, v126, v126
	v_mul_f32_e32 v123, v123, v123
	v_mul_f32_e32 v124, v124, v124
	v_mul_f32_e32 v125, v125, v125
	v_cvt_pk_bf16_f32 v122, v126, v122
	v_pk_fma_f32 v[120:121], v[120:121], v[132:133], v[48:49] op_sel_hi:[1,0,1]
	v_pk_fma_f32 v[118:119], v[118:119], v[132:133], v[46:47] op_sel_hi:[1,0,1]
	v_max_f32_e32 v114, 0, v114
	v_max_f32_e32 v115, 0, v115
	v_max_f32_e32 v116, 0, v116
	v_cvt_pk_bf16_f32 v123, v123, v124
	v_cvt_pk_bf16_f32 v124, v133, v127
	v_cvt_pk_bf16_f32 v125, v128, v125
	global_store_dwordx4 v[130:131], v[122:125], off
	v_max_f32_e32 v117, 0, v117
	v_max_f32_e32 v118, 0, v118
	v_mul_f32_e32 v122, v114, v114
	v_max_f32_e32 v114, 0, v119
	v_mul_f32_e32 v119, v115, v115
	v_max_f32_e32 v115, 0, v120
	v_mul_f32_e32 v120, v116, v116
	v_max_f32_e32 v116, 0, v121
	v_mul_f32_e32 v114, v114, v114
	v_mul_f32_e32 v115, v115, v115
	v_mul_f32_e32 v116, v116, v116
	v_mul_f32_e32 v117, v117, v117
	v_mul_f32_e32 v118, v118, v118
	v_cvt_pk_bf16_f32 v114, v118, v114
	v_cvt_pk_bf16_f32 v115, v115, v116
	v_cvt_pk_bf16_f32 v116, v122, v119
	v_cvt_pk_bf16_f32 v117, v120, v117
	global_store_dwordx4 v[130:131], v[114:117], off offset:256
	global_load_dword v116, v[158:159], off offset:128
	s_nop 0
	v_or_b32_e32 v114, 32, v160
	v_ashrrev_i32_e32 v115, 31, v114
	v_lshlrev_b64 v[114:115], 13, v[114:115]
	v_lshl_add_u64 v[114:115], s[86:87], 0, v[114:115]
	v_lshl_add_u64 v[114:115], v[114:115], 0, v[178:179]
	s_waitcnt vmcnt(0)
; DI unsigned pk2(float lo, float hi) { return pg8::cvt_pk_bf16(lo, hi); }
;     DI void operator()(const f32x4 (&acc)[2][2][4][2], const Unit& u, int wr, int wc, int fr, int fq) const {
;     ...
;         for (int ai = 0; ai < 2; ++ai)
; #pragma unroll
;             for (int m = 0; m < 4; ++m) { bf16* rowp = O + (size_t)(row0 + ai * 128 + m * 16) * 4096 + col0;
;                 const float rstd = rsqrtf(rowss[row0 + ai * 128 + m * 16] * (1.0f / 1024.0f) + 1e-6f);
; #pragma unroll
;                 for (int bj = 0; bj < 2; ++bj) { f32x4 v0 = acc[ai][bj][m][0] * rstd + bs[bj][0], v1 = acc[ai][bj][m][1] * rstd + bs[bj][1];
; #pragma unroll
;                     for (int i = 0; i < 4; ++i) { float a = fmaxf(v0[i], 0.f), b = fmaxf(v1[i], 0.f); v0[i] = a * a; v1[i] = b * b; }
;                     v4u w; w.x = pk2(v0[0], v0[1]); w.y = pk2(v0[2], v0[3]); w.z = pk2(v1[0], v1[1]); w.w = pk2(v1[2], v1[3]);
;                     *(v4u*)(rowp + bj * 128) = w; } }
	v_fmamk_f32 v116, v116, 0x3a800000, v192
	v_cmp_gt_f32_e32 vcc, s17, v116
	v_mul_f32_e32 v117, 0x4b800000, v116
	s_nop 0
	v_cndmask_b32_e32 v116, v116, v117, vcc
	v_rsq_f32_e32 v116, v116
	s_nop 0
	v_mul_f32_e32 v117, 0x45800000, v116
	v_cndmask_b32_e32 v116, v116, v117, vcc
	v_pk_fma_f32 v[106:107], v[106:107], v[116:117], v[58:59] op_sel_hi:[1,0,1]
	v_pk_fma_f32 v[110:111], v[110:111], v[116:117], v[62:63] op_sel_hi:[1,0,1]
	v_pk_fma_f32 v[108:109], v[108:109], v[116:117], v[60:61] op_sel_hi:[1,0,1]
	v_max_f32_e32 v106, 0, v106
	v_pk_fma_f32 v[112:113], v[112:113], v[116:117], v[64:65] op_sel_hi:[1,0,1]
	v_mul_f32_e32 v117, v106, v106
	v_max_f32_e32 v106, 0, v111
	v_max_f32_e32 v107, 0, v107
	v_max_f32_e32 v108, 0, v108
	v_max_f32_e32 v110, 0, v110
	v_mul_f32_e32 v106, v106, v106
	v_mul_f32_e32 v111, v107, v107
	v_max_f32_e32 v107, 0, v112
	v_mul_f32_e32 v112, v108, v108
	v_max_f32_e32 v108, 0, v113
	v_max_f32_e32 v109, 0, v109
	v_pk_fma_f32 v[100:101], v[100:101], v[116:117], v[44:45] op_sel_hi:[1,0,1]
	v_pk_fma_f32 v[98:99], v[98:99], v[116:117], v[42:43] op_sel_hi:[1,0,1]
	v_mul_f32_e32 v110, v110, v110
	v_mul_f32_e32 v107, v107, v107
	v_mul_f32_e32 v108, v108, v108
	v_mul_f32_e32 v109, v109, v109
	v_cvt_pk_bf16_f32 v106, v110, v106
	v_pk_fma_f32 v[104:105], v[104:105], v[116:117], v[48:49] op_sel_hi:[1,0,1]
	v_pk_fma_f32 v[102:103], v[102:103], v[116:117], v[46:47] op_sel_hi:[1,0,1]
	v_max_f32_e32 v98, 0, v98
	v_max_f32_e32 v99, 0, v99
	v_max_f32_e32 v100, 0, v100
	v_cvt_pk_bf16_f32 v107, v107, v108
	v_cvt_pk_bf16_f32 v108, v117, v111
	v_cvt_pk_bf16_f32 v109, v112, v109
	global_store_dwordx4 v[114:115], v[106:109], off
	v_max_f32_e32 v101, 0, v101
	v_max_f32_e32 v102, 0, v102
	v_mul_f32_e32 v106, v98, v98
	v_max_f32_e32 v98, 0, v103
	v_mul_f32_e32 v103, v99, v99
	v_max_f32_e32 v99, 0, v104
	v_mul_f32_e32 v104, v100, v100
	v_max_f32_e32 v100, 0, v105
	v_mul_f32_e32 v98, v98, v98
	v_mul_f32_e32 v99, v99, v99
	v_mul_f32_e32 v100, v100, v100
	v_mul_f32_e32 v101, v101, v101
	v_mul_f32_e32 v102, v102, v102
	v_cvt_pk_bf16_f32 v98, v102, v98
	v_cvt_pk_bf16_f32 v99, v99, v100
	v_cvt_pk_bf16_f32 v100, v106, v103
	v_cvt_pk_bf16_f32 v101, v104, v101
	global_store_dwordx4 v[114:115], v[98:101], off offset:256
	global_load_dword v100, v[158:159], off offset:192
	s_nop 0
	v_or_b32_e32 v98, 48, v160
	v_ashrrev_i32_e32 v99, 31, v98
	v_lshlrev_b64 v[98:99], 13, v[98:99]
	v_lshl_add_u64 v[98:99], s[86:87], 0, v[98:99]
	v_lshl_add_u64 v[98:99], v[98:99], 0, v[178:179]
	s_waitcnt vmcnt(0)
	v_fmamk_f32 v100, v100, 0x3a800000, v192
	v_cmp_gt_f32_e32 vcc, s17, v100
	v_mul_f32_e32 v101, 0x4b800000, v100
	s_nop 0
	v_cndmask_b32_e32 v100, v100, v101, vcc
	v_rsq_f32_e32 v100, v100
	s_nop 0
	v_mul_f32_e32 v101, 0x45800000, v100
	v_cndmask_b32_e32 v100, v100, v101, vcc
	v_pk_fma_f32 v[90:91], v[90:91], v[100:101], v[58:59] op_sel_hi:[1,0,1]
	v_pk_fma_f32 v[94:95], v[94:95], v[100:101], v[62:63] op_sel_hi:[1,0,1]
	v_pk_fma_f32 v[92:93], v[92:93], v[100:101], v[60:61] op_sel_hi:[1,0,1]
	v_max_f32_e32 v90, 0, v90
	v_pk_fma_f32 v[96:97], v[96:97], v[100:101], v[64:65] op_sel_hi:[1,0,1]
	v_mul_f32_e32 v101, v90, v90
	v_max_f32_e32 v90, 0, v95
	v_max_f32_e32 v91, 0, v91
	v_max_f32_e32 v92, 0, v92
	v_max_f32_e32 v94, 0, v94
	v_mul_f32_e32 v90, v90, v90
	v_mul_f32_e32 v95, v91, v91
	v_max_f32_e32 v91, 0, v96
	v_mul_f32_e32 v96, v92, v92
	v_max_f32_e32 v92, 0, v97
	v_max_f32_e32 v93, 0, v93
	v_pk_fma_f32 v[84:85], v[84:85], v[100:101], v[44:45] op_sel_hi:[1,0,1]
	v_pk_fma_f32 v[82:83], v[82:83], v[100:101], v[42:43] op_sel_hi:[1,0,1]
	v_mul_f32_e32 v94, v94, v94
	v_mul_f32_e32 v91, v91, v91
	v_mul_f32_e32 v92, v92, v92
	v_mul_f32_e32 v93, v93, v93
	v_cvt_pk_bf16_f32 v90, v94, v90
	v_pk_fma_f32 v[88:89], v[88:89], v[100:101], v[48:49] op_sel_hi:[1,0,1]
	v_pk_fma_f32 v[86:87], v[86:87], v[100:101], v[46:47] op_sel_hi:[1,0,1]
	v_max_f32_e32 v82, 0, v82
	v_max_f32_e32 v83, 0, v83
	v_max_f32_e32 v84, 0, v84
	v_cvt_pk_bf16_f32 v91, v91, v92
	v_cvt_pk_bf16_f32 v92, v101, v95
	v_cvt_pk_bf16_f32 v93, v96, v93
	global_store_dwordx4 v[98:99], v[90:93], off
	v_max_f32_e32 v85, 0, v85
	v_max_f32_e32 v86, 0, v86
	v_mul_f32_e32 v90, v82, v82
	v_max_f32_e32 v82, 0, v87
	v_mul_f32_e32 v87, v83, v83
	v_max_f32_e32 v83, 0, v88
	v_mul_f32_e32 v88, v84, v84
	v_max_f32_e32 v84, 0, v89
	v_mul_f32_e32 v82, v82, v82
	v_mul_f32_e32 v83, v83, v83
	v_mul_f32_e32 v84, v84, v84
	v_mul_f32_e32 v85, v85, v85
	v_mul_f32_e32 v86, v86, v86
	v_cvt_pk_bf16_f32 v82, v86, v82
	v_cvt_pk_bf16_f32 v83, v83, v84
	v_cvt_pk_bf16_f32 v84, v90, v87
	v_cvt_pk_bf16_f32 v85, v88, v85
	global_store_dwordx4 v[98:99], v[82:85], off offset:256
	global_load_dword v84, v[158:159], off offset:512
	s_nop 0
	v_lshl_add_u64 v[82:83], v[156:157], 0, s[2:3]
	s_mov_b32 s2, 0x100000
	s_waitcnt vmcnt(0)
; DI unsigned pk2(float lo, float hi) { return pg8::cvt_pk_bf16(lo, hi); }
;     DI void operator()(const f32x4 (&acc)[2][2][4][2], const Unit& u, int wr, int wc, int fr, int fq) const {
;     ...
;         for (int ai = 0; ai < 2; ++ai)
; #pragma unroll
;             for (int m = 0; m < 4; ++m) { bf16* rowp = O + (size_t)(row0 + ai * 128 + m * 16) * 4096 + col0;
;                 const float rstd = rsqrtf(rowss[row0 + ai * 128 + m * 16] * (1.0f / 1024.0f) + 1e-6f);
; #pragma unroll
;                 for (int bj = 0; bj < 2; ++bj) { f32x4 v0 = acc[ai][bj][m][0] * rstd + bs[bj][0], v1 = acc[ai][bj][m][1] * rstd + bs[bj][1];
; #pragma unroll
;                     for (int i = 0; i < 4; ++i) { float a = fmaxf(v0[i], 0.f), b = fmaxf(v1[i], 0.f); v0[i] = a * a; v1[i] = b * b; }
;                     v4u w; w.x = pk2(v0[0], v0[1]); w.y = pk2(v0[2], v0[3]); w.z = pk2(v1[0], v1[1]); w.w = pk2(v1[2], v1[3]);
;                     *(v4u*)(rowp + bj * 128) = w; } }
	v_fmamk_f32 v84, v84, 0x3a800000, v192
	v_cmp_gt_f32_e32 vcc, s17, v84
	v_mul_f32_e32 v85, 0x4b800000, v84
	s_nop 0
	v_cndmask_b32_e32 v84, v84, v85, vcc
	v_rsq_f32_e32 v84, v84
	s_nop 0
	v_mul_f32_e32 v85, 0x45800000, v84
	v_cndmask_b32_e32 v84, v84, v85, vcc
	v_pk_fma_f32 v[74:75], v[74:75], v[84:85], v[58:59] op_sel_hi:[1,0,1]
	v_pk_fma_f32 v[78:79], v[78:79], v[84:85], v[62:63] op_sel_hi:[1,0,1]
	v_pk_fma_f32 v[76:77], v[76:77], v[84:85], v[60:61] op_sel_hi:[1,0,1]
	v_max_f32_e32 v74, 0, v74
	v_pk_fma_f32 v[80:81], v[80:81], v[84:85], v[64:65] op_sel_hi:[1,0,1]
	v_max_f32_e32 v78, 0, v78
	v_mul_f32_e32 v85, v74, v74
	v_max_f32_e32 v74, 0, v79
	v_max_f32_e32 v75, 0, v75
	v_max_f32_e32 v76, 0, v76
	v_mul_f32_e32 v78, v78, v78
	v_mul_f32_e32 v74, v74, v74
	v_mul_f32_e32 v79, v75, v75
	v_max_f32_e32 v75, 0, v80
	v_mul_f32_e32 v80, v76, v76
	v_max_f32_e32 v76, 0, v81
	v_mul_f32_e32 v75, v75, v75
	v_max_f32_e32 v77, 0, v77
	v_mul_f32_e32 v76, v76, v76
	v_cvt_pk_bf16_f32 v74, v78, v74
	v_add_co_u32_e32 v78, vcc, s2, v156
	v_pk_fma_f32 v[68:69], v[68:69], v[84:85], v[44:45] op_sel_hi:[1,0,1]
	v_pk_fma_f32 v[66:67], v[66:67], v[84:85], v[42:43] op_sel_hi:[1,0,1]
	v_mul_f32_e32 v77, v77, v77
	v_cvt_pk_bf16_f32 v75, v75, v76
	v_cvt_pk_bf16_f32 v76, v85, v79
	v_addc_co_u32_e32 v79, vcc, 0, v157, vcc
	v_pk_fma_f32 v[72:73], v[72:73], v[84:85], v[48:49] op_sel_hi:[1,0,1]
	v_pk_fma_f32 v[70:71], v[70:71], v[84:85], v[46:47] op_sel_hi:[1,0,1]
	v_max_f32_e32 v66, 0, v66
	v_max_f32_e32 v67, 0, v67
	v_max_f32_e32 v68, 0, v68
	v_cvt_pk_bf16_f32 v77, v80, v77
	global_store_dwordx4 v[78:79], v[74:77], off
	v_max_f32_e32 v69, 0, v69
	v_max_f32_e32 v70, 0, v70
	v_mul_f32_e32 v74, v66, v66
	v_max_f32_e32 v66, 0, v71
	v_mul_f32_e32 v71, v67, v67
	v_max_f32_e32 v67, 0, v72
	v_mul_f32_e32 v72, v68, v68
	v_max_f32_e32 v68, 0, v73
	v_mul_f32_e32 v66, v66, v66
	v_mul_f32_e32 v67, v67, v67
	v_mul_f32_e32 v68, v68, v68
	v_mul_f32_e32 v69, v69, v69
	v_mul_f32_e32 v70, v70, v70
	v_cvt_pk_bf16_f32 v66, v70, v66
	v_cvt_pk_bf16_f32 v67, v67, v68
	v_cvt_pk_bf16_f32 v68, v74, v71
	v_cvt_pk_bf16_f32 v69, v72, v69
	global_store_dwordx4 v[82:83], v[66:69], off offset:256
	global_load_dword v68, v[158:159], off offset:576
	s_mov_b64 s[2:3], 0x120000
	v_lshl_add_u64 v[66:67], v[156:157], 0, s[2:3]
	s_mov_b32 s2, 0x120000
	s_waitcnt vmcnt(0)
	v_fmamk_f32 v68, v68, 0x3a800000, v192
	v_cmp_gt_f32_e32 vcc, s17, v68
	v_mul_f32_e32 v69, 0x4b800000, v68
	s_nop 0
	v_cndmask_b32_e32 v68, v68, v69, vcc
	v_rsq_f32_e32 v68, v68
	s_nop 0
	v_mul_f32_e32 v69, 0x45800000, v68
	v_cndmask_b32_e32 v68, v68, v69, vcc
	v_pk_fma_f32 v[50:51], v[50:51], v[68:69], v[58:59] op_sel_hi:[1,0,1]
	v_pk_fma_f32 v[54:55], v[54:55], v[68:69], v[62:63] op_sel_hi:[1,0,1]
	v_pk_fma_f32 v[52:53], v[52:53], v[68:69], v[60:61] op_sel_hi:[1,0,1]
	v_max_f32_e32 v50, 0, v50
	v_pk_fma_f32 v[56:57], v[56:57], v[68:69], v[64:65] op_sel_hi:[1,0,1]
	v_max_f32_e32 v54, 0, v54
	v_mul_f32_e32 v69, v50, v50
	v_max_f32_e32 v50, 0, v55
	v_max_f32_e32 v51, 0, v51
	v_max_f32_e32 v52, 0, v52
	v_mul_f32_e32 v54, v54, v54
	v_mul_f32_e32 v50, v50, v50
	v_mul_f32_e32 v55, v51, v51
	v_max_f32_e32 v51, 0, v56
	v_mul_f32_e32 v56, v52, v52
	v_max_f32_e32 v52, 0, v57
	v_mul_f32_e32 v51, v51, v51
	v_max_f32_e32 v53, 0, v53
	v_mul_f32_e32 v52, v52, v52
	v_cvt_pk_bf16_f32 v50, v54, v50
	v_add_co_u32_e32 v54, vcc, s2, v156
	v_pk_fma_f32 v[36:37], v[36:37], v[68:69], v[44:45] op_sel_hi:[1,0,1]
	v_pk_fma_f32 v[34:35], v[34:35], v[68:69], v[42:43] op_sel_hi:[1,0,1]
	v_mul_f32_e32 v53, v53, v53
	v_cvt_pk_bf16_f32 v51, v51, v52
	v_cvt_pk_bf16_f32 v52, v69, v55
	v_addc_co_u32_e32 v55, vcc, 0, v157, vcc
	v_pk_fma_f32 v[40:41], v[40:41], v[68:69], v[48:49] op_sel_hi:[1,0,1]
	v_pk_fma_f32 v[38:39], v[38:39], v[68:69], v[46:47] op_sel_hi:[1,0,1]
	v_max_f32_e32 v34, 0, v34
	v_max_f32_e32 v35, 0, v35
	v_max_f32_e32 v36, 0, v36
	v_cvt_pk_bf16_f32 v53, v56, v53
	global_store_dwordx4 v[54:55], v[50:53], off
	v_max_f32_e32 v37, 0, v37
	v_max_f32_e32 v38, 0, v38
	v_mul_f32_e32 v50, v34, v34
	v_max_f32_e32 v34, 0, v39
	v_mul_f32_e32 v39, v35, v35
	v_max_f32_e32 v35, 0, v40
	v_mul_f32_e32 v40, v36, v36
	v_max_f32_e32 v36, 0, v41
	v_mul_f32_e32 v34, v34, v34
	v_mul_f32_e32 v35, v35, v35
	v_mul_f32_e32 v36, v36, v36
	v_mul_f32_e32 v37, v37, v37
	v_mul_f32_e32 v38, v38, v38
	v_cvt_pk_bf16_f32 v34, v38, v34
	v_cvt_pk_bf16_f32 v35, v35, v36
	v_cvt_pk_bf16_f32 v36, v50, v39
	v_cvt_pk_bf16_f32 v37, v40, v37
	global_store_dwordx4 v[66:67], v[34:37], off offset:256
	global_load_dword v36, v[158:159], off offset:640
	s_mov_b64 s[2:3], 0x140000
	v_lshl_add_u64 v[34:35], v[156:157], 0, s[2:3]
	s_mov_b32 s2, 0x140000
	s_waitcnt vmcnt(0)
; #define PG8_BAR __builtin_amdgcn_s_barrier()
; DI unsigned pk2(float lo, float hi) { return pg8::cvt_pk_bf16(lo, hi); }
; template <class Epi, class Sched, bool ALIGN_EPI = false, bool SP2 = false>
; __device__ __forceinline__ void gemm_phase(PG8_LAS unsigned char* lds, const Gemm g, const Sched& S, const Epi& E) {
;     ...
;         if (!has_next) break;
; #pragma unroll
;         for (int a = 0; a < 2; ++a)
; #pragma unroll
;             for (int b = 0; b < 2; ++b)
; #pragma unroll
;                 for (int m = 0; m < 4; ++m)
; #pragma unroll
;                     for (int n = 0; n < 2; ++n) acc[a][b][m][n] = (f32x4){0.f, 0.f, 0.f, 0.f};
;         cur = nxt; cA = nA; cB = nB; ++ui;
;         if constexpr (ALIGN_EPI) { if (wr == 1) PG8_BAR; }
;     DI void operator()(const f32x4 (&acc)[2][2][4][2], const Unit& u, int wr, int wc, int fr, int fq) const {
;     ...
;         for (int ai = 0; ai < 2; ++ai)
; #pragma unroll
;             for (int m = 0; m < 4; ++m) { bf16* rowp = O + (size_t)(row0 + ai * 128 + m * 16) * 4096 + col0;
;                 const float rstd = rsqrtf(rowss[row0 + ai * 128 + m * 16] * (1.0f / 1024.0f) + 1e-6f);
; #pragma unroll
;                 for (int bj = 0; bj < 2; ++bj) { f32x4 v0 = acc[ai][bj][m][0] * rstd + bs[bj][0], v1 = acc[ai][bj][m][1] * rstd + bs[bj][1];
; #pragma unroll
;                     for (int i = 0; i < 4; ++i) { float a = fmaxf(v0[i], 0.f), b = fmaxf(v1[i], 0.f); v0[i] = a * a; v1[i] = b * b; }
;                     v4u w; w.x = pk2(v0[0], v0[1]); w.y = pk2(v0[2], v0[3]); w.z = pk2(v1[0], v1[1]); w.w = pk2(v1[2], v1[3]);
;                     *(v4u*)(rowp + bj * 128) = w; } }
	v_fmamk_f32 v36, v36, 0x3a800000, v192
	v_cmp_gt_f32_e32 vcc, s17, v36
	v_mul_f32_e32 v37, 0x4b800000, v36
	s_nop 0
	v_cndmask_b32_e32 v36, v36, v37, vcc
	v_rsq_f32_e32 v36, v36
	s_nop 0
	v_mul_f32_e32 v37, 0x45800000, v36
	v_cndmask_b32_e32 v36, v36, v37, vcc
	v_pk_fma_f32 v[26:27], v[26:27], v[36:37], v[58:59] op_sel_hi:[1,0,1]
	v_pk_fma_f32 v[30:31], v[30:31], v[36:37], v[62:63] op_sel_hi:[1,0,1]
	v_pk_fma_f32 v[28:29], v[28:29], v[36:37], v[60:61] op_sel_hi:[1,0,1]
	v_max_f32_e32 v26, 0, v26
	v_pk_fma_f32 v[32:33], v[32:33], v[36:37], v[64:65] op_sel_hi:[1,0,1]
	v_max_f32_e32 v30, 0, v30
	v_mul_f32_e32 v37, v26, v26
	v_max_f32_e32 v26, 0, v31
	v_max_f32_e32 v27, 0, v27
	v_max_f32_e32 v28, 0, v28
	v_mul_f32_e32 v30, v30, v30
	v_mul_f32_e32 v26, v26, v26
	v_mul_f32_e32 v31, v27, v27
	v_max_f32_e32 v27, 0, v32
	v_mul_f32_e32 v32, v28, v28
	v_max_f32_e32 v28, 0, v33
	v_mul_f32_e32 v27, v27, v27
	v_max_f32_e32 v29, 0, v29
	v_mul_f32_e32 v28, v28, v28
	v_cvt_pk_bf16_f32 v26, v30, v26
	v_add_co_u32_e32 v30, vcc, s2, v156
	v_pk_fma_f32 v[20:21], v[20:21], v[36:37], v[44:45] op_sel_hi:[1,0,1]
	v_pk_fma_f32 v[18:19], v[18:19], v[36:37], v[42:43] op_sel_hi:[1,0,1]
	v_mul_f32_e32 v29, v29, v29
	v_cvt_pk_bf16_f32 v27, v27, v28
	v_cvt_pk_bf16_f32 v28, v37, v31
	v_addc_co_u32_e32 v31, vcc, 0, v157, vcc
	v_pk_fma_f32 v[24:25], v[24:25], v[36:37], v[48:49] op_sel_hi:[1,0,1]
	v_pk_fma_f32 v[22:23], v[22:23], v[36:37], v[46:47] op_sel_hi:[1,0,1]
	v_max_f32_e32 v18, 0, v18
	v_max_f32_e32 v19, 0, v19
	v_max_f32_e32 v20, 0, v20
	v_cvt_pk_bf16_f32 v29, v32, v29
	global_store_dwordx4 v[30:31], v[26:29], off
	v_max_f32_e32 v21, 0, v21
	v_max_f32_e32 v22, 0, v22
	v_mul_f32_e32 v26, v18, v18
	v_max_f32_e32 v18, 0, v23
	v_mul_f32_e32 v23, v19, v19
	v_max_f32_e32 v19, 0, v24
	v_mul_f32_e32 v24, v20, v20
	v_max_f32_e32 v20, 0, v25
	v_mul_f32_e32 v18, v18, v18
	v_mul_f32_e32 v19, v19, v19
	v_mul_f32_e32 v20, v20, v20
	v_mul_f32_e32 v21, v21, v21
	v_mul_f32_e32 v22, v22, v22
	v_cvt_pk_bf16_f32 v18, v22, v18
	v_cvt_pk_bf16_f32 v19, v19, v20
	v_cvt_pk_bf16_f32 v20, v26, v23
	v_cvt_pk_bf16_f32 v21, v24, v21
	global_store_dwordx4 v[34:35], v[18:21], off offset:256
	global_load_dword v20, v[158:159], off offset:704
	s_mov_b64 s[2:3], 0x160000
	v_lshl_add_u64 v[18:19], v[156:157], 0, s[2:3]
	s_mov_b32 s2, 0x160000
	s_waitcnt vmcnt(0)
	v_fmamk_f32 v20, v20, 0x3a800000, v192
	v_cmp_gt_f32_e32 vcc, s17, v20
	v_mul_f32_e32 v21, 0x4b800000, v20
	s_nop 0
	v_cndmask_b32_e32 v20, v20, v21, vcc
	v_rsq_f32_e32 v20, v20
	s_nop 0
	v_mul_f32_e32 v21, 0x45800000, v20
	v_cndmask_b32_e32 v20, v20, v21, vcc
	v_pk_fma_f32 v[10:11], v[10:11], v[20:21], v[58:59] op_sel_hi:[1,0,1]
	v_pk_fma_f32 v[14:15], v[14:15], v[20:21], v[62:63] op_sel_hi:[1,0,1]
	v_pk_fma_f32 v[12:13], v[12:13], v[20:21], v[60:61] op_sel_hi:[1,0,1]
	v_max_f32_e32 v10, 0, v10
	v_pk_fma_f32 v[16:17], v[16:17], v[20:21], v[64:65] op_sel_hi:[1,0,1]
	v_max_f32_e32 v14, 0, v14
	v_mul_f32_e32 v21, v10, v10
	v_max_f32_e32 v10, 0, v15
	v_max_f32_e32 v11, 0, v11
	v_max_f32_e32 v12, 0, v12
	v_mul_f32_e32 v14, v14, v14
	v_mul_f32_e32 v10, v10, v10
	v_mul_f32_e32 v15, v11, v11
	v_max_f32_e32 v11, 0, v16
	v_mul_f32_e32 v16, v12, v12
	v_max_f32_e32 v12, 0, v17
	v_mul_f32_e32 v11, v11, v11
	v_max_f32_e32 v13, 0, v13
	v_mul_f32_e32 v12, v12, v12
	v_cvt_pk_bf16_f32 v10, v14, v10
	v_add_co_u32_e32 v14, vcc, s2, v156
	v_pk_fma_f32 v[4:5], v[4:5], v[20:21], v[44:45] op_sel_hi:[1,0,1]
	v_pk_fma_f32 v[2:3], v[2:3], v[20:21], v[42:43] op_sel_hi:[1,0,1]
	v_mul_f32_e32 v13, v13, v13
	v_cvt_pk_bf16_f32 v11, v11, v12
	v_cvt_pk_bf16_f32 v12, v21, v15
	v_addc_co_u32_e32 v15, vcc, 0, v157, vcc
	v_pk_fma_f32 v[8:9], v[8:9], v[20:21], v[48:49] op_sel_hi:[1,0,1]
	v_pk_fma_f32 v[6:7], v[6:7], v[20:21], v[46:47] op_sel_hi:[1,0,1]
	v_max_f32_e32 v2, 0, v2
	v_max_f32_e32 v3, 0, v3
	v_max_f32_e32 v4, 0, v4
	v_cvt_pk_bf16_f32 v13, v16, v13
	global_store_dwordx4 v[14:15], v[10:13], off
	v_max_f32_e32 v5, 0, v5
	v_max_f32_e32 v6, 0, v6
	v_mul_f32_e32 v10, v2, v2
	v_max_f32_e32 v2, 0, v7
	v_mul_f32_e32 v7, v3, v3
	v_max_f32_e32 v3, 0, v8
	v_mul_f32_e32 v8, v4, v4
	v_max_f32_e32 v4, 0, v9
	v_mul_f32_e32 v2, v2, v2
	v_mul_f32_e32 v3, v3, v3
	v_mul_f32_e32 v4, v4, v4
	v_mul_f32_e32 v5, v5, v5
	s_mov_b64 s[2:3], -1
	s_andn2_b64 vcc, exec, s[4:5]
	v_mul_f32_e32 v6, v6, v6
	v_cvt_pk_bf16_f32 v2, v6, v2
	v_cvt_pk_bf16_f32 v3, v3, v4
	v_cvt_pk_bf16_f32 v4, v10, v7
	v_cvt_pk_bf16_f32 v5, v8, v5
	global_store_dwordx4 v[18:19], v[2:5], off offset:256
	s_cbranch_vccnz .LBB0_731
	s_andn2_b64 vcc, exec, s[6:7]
	s_cbranch_vccnz .LBB0_730
	s_barrier
	s_branch .LBB0_730

;     DI void operator()(const f32x4 (&acc)[2][2][4][2], const Unit& u, int wr, int wc, int fr, int fq) const {
;         const int row0 = u.pm * 256 + wr * 64 + fr, col0 = u.pn * 256 + wc * 32 + 8 * fq;
;         const int b = (grow0 + u.pm * 256) >> 11;
;         f32x4 g[2][2];
; #pragma unroll
;         for (int bj = 0; bj < 2; ++bj) { const float* gp = gate + (size_t)b * 6144 + col0 + bj * 128; g[bj][0] = *(const f32x4*)gp; g[bj][1] = *(const f32x4*)(gp + 4); }
; #pragma unroll
;         for (int ai = 0; ai < 2; ++ai)
; #pragma unroll
;             for (int m = 0; m < 4; ++m) { const size_t r = (size_t)(row0 + ai * 128 + m * 16);
; #pragma unroll
;                 for (int bj = 0; bj < 2; ++bj) { const size_t off = r * 1024 + col0 + bj * 128;
;                     f32x4 v0 = *(const f32x4*)(base + off), v1 = *(const f32x4*)(base + off + 4);
;                     v0 += g[bj][0] * acc[ai][bj][m][0]; v1 += g[bj][1] * acc[ai][bj][m][1];
;                     *(f32x4*)(out + off) = v0; *(f32x4*)(out + off + 4) = v1; } }
.LBB0_815:
	s_lshl_b32 s7, s31, 8
	v_readlane_b32 s16, v254, 56
	s_add_i32 s11, s7, s16
	v_readlane_b32 s17, v254, 57
	s_ashr_i32 s11, s11, 11
	v_add_u32_e32 v164, s7, v158
	v_lshl_or_b32 v50, s30, 8, v160
	s_mul_hi_i32 s17, s11, 0x6000
	s_mulk_i32 s11, 0x6000
	v_readlane_b32 s16, v252, 33
	v_ashrrev_i32_e32 v165, 31, v164
	s_add_u32 s16, s16, s11
	v_readlane_b32 s11, v252, 34
	v_ashrrev_i32_e32 v51, 31, v50
	v_lshlrev_b64 v[156:157], 12, v[164:165]
	s_addc_u32 s17, s11, s17
	v_lshlrev_b64 v[162:163], 2, v[50:51]
	v_lshl_add_u64 v[156:157], s[8:9], 0, v[156:157]
	v_lshl_add_u64 v[54:55], s[16:17], 0, v[162:163]
	v_lshl_add_u64 v[156:157], v[156:157], 0, v[162:163]
	global_load_dwordx4 v[74:77], v[54:55], off offset:16
	global_load_dwordx4 v[78:81], v[54:55], off
	global_load_dwordx4 v[50:53], v[54:55], off offset:528
	s_nop 0
	global_load_dwordx4 v[54:57], v[54:55], off offset:512
	global_load_dwordx4 v[208:211], v[156:157], off
	global_load_dwordx4 v[212:215], v[156:157], off offset:16
	global_load_dwordx4 v[216:219], v[156:157], off offset:512
	global_load_dwordx4 v[220:223], v[156:157], off offset:528
	s_mov_b64 s[98:99], 0x10000
	v_lshl_add_u64 v[200:201], v[156:157], 0, s[98:99]
	global_load_dwordx4 v[224:227], v[200:201], off
	global_load_dwordx4 v[228:231], v[200:201], off offset:16
	global_load_dwordx4 v[232:235], v[200:201], off offset:512
	global_load_dwordx4 v[236:239], v[200:201], off offset:528
	s_waitcnt vmcnt(6)
	v_pk_fma_f32 v[208:209], v[142:143], v[78:79], v[208:209]
	v_pk_fma_f32 v[210:211], v[144:145], v[80:81], v[210:211]
	v_pk_fma_f32 v[212:213], v[138:139], v[74:75], v[212:213]
	v_pk_fma_f32 v[214:215], v[140:141], v[76:77], v[214:215]
	global_store_dwordx4 v[156:157], v[208:211], off
	global_store_dwordx4 v[156:157], v[212:215], off offset:16
	s_nop 1
	s_mov_b64 s[98:99], 0x20000
	v_lshl_add_u64 v[200:201], v[156:157], 0, s[98:99]
	global_load_dwordx4 v[208:211], v[200:201], off
	global_load_dwordx4 v[212:215], v[200:201], off offset:16
	s_waitcnt vmcnt(8)
	v_pk_fma_f32 v[216:217], v[134:135], v[54:55], v[216:217]
	v_pk_fma_f32 v[218:219], v[136:137], v[56:57], v[218:219]
	v_pk_fma_f32 v[220:221], v[130:131], v[50:51], v[220:221]
	v_pk_fma_f32 v[222:223], v[132:133], v[52:53], v[222:223]
	global_store_dwordx4 v[156:157], v[216:219], off offset:512
	global_store_dwordx4 v[156:157], v[220:223], off offset:528
	s_nop 1
	global_load_dwordx4 v[216:219], v[200:201], off offset:512
	global_load_dwordx4 v[220:223], v[200:201], off offset:528
	s_waitcnt vmcnt(10)
	v_pk_fma_f32 v[224:225], v[126:127], v[78:79], v[224:225]
	v_pk_fma_f32 v[226:227], v[128:129], v[80:81], v[226:227]
	v_pk_fma_f32 v[228:229], v[122:123], v[74:75], v[228:229]
	v_pk_fma_f32 v[230:231], v[124:125], v[76:77], v[230:231]
	s_mov_b64 s[98:99], 0x10000
	v_lshl_add_u64 v[202:203], v[156:157], 0, s[98:99]
	global_store_dwordx4 v[202:203], v[224:227], off
	global_store_dwordx4 v[202:203], v[228:231], off offset:16
	s_nop 1
	s_mov_b64 s[98:99], 0x30000
	v_lshl_add_u64 v[200:201], v[156:157], 0, s[98:99]
	global_load_dwordx4 v[224:227], v[200:201], off
	global_load_dwordx4 v[228:231], v[200:201], off offset:16
	s_waitcnt vmcnt(12)
	v_pk_fma_f32 v[232:233], v[110:111], v[54:55], v[232:233]
	v_pk_fma_f32 v[234:235], v[112:113], v[56:57], v[234:235]
	v_pk_fma_f32 v[236:237], v[106:107], v[50:51], v[236:237]
	v_pk_fma_f32 v[238:239], v[108:109], v[52:53], v[238:239]
	global_store_dwordx4 v[202:203], v[232:235], off offset:512
	global_store_dwordx4 v[202:203], v[236:239], off offset:528
	s_nop 1
	global_load_dwordx4 v[232:235], v[200:201], off offset:512
	global_load_dwordx4 v[236:239], v[200:201], off offset:528
	s_waitcnt vmcnt(12)
	v_pk_fma_f32 v[208:209], v[118:119], v[78:79], v[208:209]
	v_pk_fma_f32 v[210:211], v[120:121], v[80:81], v[210:211]
	v_pk_fma_f32 v[212:213], v[114:115], v[74:75], v[212:213]
	v_pk_fma_f32 v[214:215], v[116:117], v[76:77], v[214:215]
	s_mov_b64 s[98:99], 0x20000
	v_lshl_add_u64 v[202:203], v[156:157], 0, s[98:99]
	global_store_dwordx4 v[202:203], v[208:211], off
	global_store_dwordx4 v[202:203], v[212:215], off offset:16
	s_nop 1
	s_mov_b64 s[98:99], 0x80000
	v_lshl_add_u64 v[200:201], v[156:157], 0, s[98:99]
	global_load_dwordx4 v[208:211], v[200:201], off
	global_load_dwordx4 v[212:215], v[200:201], off offset:16
	s_waitcnt vmcnt(12)
	v_pk_fma_f32 v[216:217], v[94:95], v[54:55], v[216:217]
	v_pk_fma_f32 v[218:219], v[96:97], v[56:57], v[218:219]
	v_pk_fma_f32 v[220:221], v[90:91], v[50:51], v[220:221]
	v_pk_fma_f32 v[222:223], v[92:93], v[52:53], v[222:223]
	global_store_dwordx4 v[202:203], v[216:219], off offset:512
	global_store_dwordx4 v[202:203], v[220:223], off offset:528
	s_nop 1
	global_load_dwordx4 v[216:219], v[200:201], off offset:512
	global_load_dwordx4 v[220:223], v[200:201], off offset:528
	s_waitcnt vmcnt(12)
; #define PG8_BAR __builtin_amdgcn_s_barrier()
; template <class Epi, class Sched, bool ALIGN_EPI = false, bool SP2 = false>
; __device__ __forceinline__ void gemm_phase(PG8_LAS unsigned char* lds, const Gemm g, const Sched& S, const Epi& E) {
;     ...
;         if (!has_next) break;
; #pragma unroll
;         for (int a = 0; a < 2; ++a)
; #pragma unroll
;             for (int b = 0; b < 2; ++b)
; #pragma unroll
;                 for (int m = 0; m < 4; ++m)
; #pragma unroll
;                     for (int n = 0; n < 2; ++n) acc[a][b][m][n] = (f32x4){0.f, 0.f, 0.f, 0.f};
;         cur = nxt; cA = nA; cB = nB; ++ui;
;         if constexpr (ALIGN_EPI) { if (wr == 1) PG8_BAR; }
;     DI void operator()(const f32x4 (&acc)[2][2][4][2], const Unit& u, int wr, int wc, int fr, int fq) const {
;     ...
;         for (int ai = 0; ai < 2; ++ai)
; #pragma unroll
;             for (int m = 0; m < 4; ++m) { const size_t r = (size_t)(row0 + ai * 128 + m * 16);
; #pragma unroll
;                 for (int bj = 0; bj < 2; ++bj) { const size_t off = r * 1024 + col0 + bj * 128;
;                     f32x4 v0 = *(const f32x4*)(base + off), v1 = *(const f32x4*)(base + off + 4);
;                     v0 += g[bj][0] * acc[ai][bj][m][0]; v1 += g[bj][1] * acc[ai][bj][m][1];
;                     *(f32x4*)(out + off) = v0; *(f32x4*)(out + off + 4) = v1; } }
	v_pk_fma_f32 v[224:225], v[102:103], v[78:79], v[224:225]
	v_pk_fma_f32 v[226:227], v[104:105], v[80:81], v[226:227]
	v_pk_fma_f32 v[228:229], v[98:99], v[74:75], v[228:229]
	v_pk_fma_f32 v[230:231], v[100:101], v[76:77], v[230:231]
	s_mov_b64 s[98:99], 0x30000
	v_lshl_add_u64 v[202:203], v[156:157], 0, s[98:99]
	global_store_dwordx4 v[202:203], v[224:227], off
	global_store_dwordx4 v[202:203], v[228:231], off offset:16
	s_nop 1
	s_mov_b64 s[98:99], 0x90000
	v_lshl_add_u64 v[200:201], v[156:157], 0, s[98:99]
	global_load_dwordx4 v[224:227], v[200:201], off
	global_load_dwordx4 v[228:231], v[200:201], off offset:16
	s_waitcnt vmcnt(12)
	v_pk_fma_f32 v[232:233], v[86:87], v[54:55], v[232:233]
	v_pk_fma_f32 v[234:235], v[88:89], v[56:57], v[234:235]
	v_pk_fma_f32 v[236:237], v[82:83], v[50:51], v[236:237]
	v_pk_fma_f32 v[238:239], v[84:85], v[52:53], v[238:239]
	global_store_dwordx4 v[202:203], v[232:235], off offset:512
	global_store_dwordx4 v[202:203], v[236:239], off offset:528
	s_nop 1
	global_load_dwordx4 v[232:235], v[200:201], off offset:512
	global_load_dwordx4 v[236:239], v[200:201], off offset:528
	s_waitcnt vmcnt(12)
	v_pk_fma_f32 v[208:209], v[70:71], v[78:79], v[208:209]
	v_pk_fma_f32 v[210:211], v[72:73], v[80:81], v[210:211]
	v_pk_fma_f32 v[212:213], v[66:67], v[74:75], v[212:213]
	v_pk_fma_f32 v[214:215], v[68:69], v[76:77], v[214:215]
	s_mov_b64 s[98:99], 0x80000
	v_lshl_add_u64 v[202:203], v[156:157], 0, s[98:99]
	global_store_dwordx4 v[202:203], v[208:211], off
	global_store_dwordx4 v[202:203], v[212:215], off offset:16
	s_nop 1
	s_mov_b64 s[98:99], 0xa0000
	v_lshl_add_u64 v[200:201], v[156:157], 0, s[98:99]
	global_load_dwordx4 v[208:211], v[200:201], off
	global_load_dwordx4 v[212:215], v[200:201], off offset:16
	s_waitcnt vmcnt(12)
	v_pk_fma_f32 v[216:217], v[62:63], v[54:55], v[216:217]
	v_pk_fma_f32 v[218:219], v[64:65], v[56:57], v[218:219]
	v_pk_fma_f32 v[220:221], v[58:59], v[50:51], v[220:221]
	v_pk_fma_f32 v[222:223], v[60:61], v[52:53], v[222:223]
	global_store_dwordx4 v[202:203], v[216:219], off offset:512
	global_store_dwordx4 v[202:203], v[220:223], off offset:528
	s_nop 1
	global_load_dwordx4 v[216:219], v[200:201], off offset:512
	global_load_dwordx4 v[220:223], v[200:201], off offset:528
	s_waitcnt vmcnt(12)
	v_pk_fma_f32 v[224:225], v[46:47], v[78:79], v[224:225]
	v_pk_fma_f32 v[226:227], v[48:49], v[80:81], v[226:227]
	v_pk_fma_f32 v[228:229], v[42:43], v[74:75], v[228:229]
	v_pk_fma_f32 v[230:231], v[44:45], v[76:77], v[230:231]
	s_mov_b64 s[98:99], 0x90000
	v_lshl_add_u64 v[202:203], v[156:157], 0, s[98:99]
	global_store_dwordx4 v[202:203], v[224:227], off
	global_store_dwordx4 v[202:203], v[228:231], off offset:16
	s_nop 1
	s_mov_b64 s[98:99], 0xb0000
	v_lshl_add_u64 v[200:201], v[156:157], 0, s[98:99]
	global_load_dwordx4 v[224:227], v[200:201], off
	global_load_dwordx4 v[228:231], v[200:201], off offset:16
	s_waitcnt vmcnt(12)
	v_pk_fma_f32 v[232:233], v[38:39], v[54:55], v[232:233]
	v_pk_fma_f32 v[234:235], v[40:41], v[56:57], v[234:235]
	v_pk_fma_f32 v[236:237], v[34:35], v[50:51], v[236:237]
	v_pk_fma_f32 v[238:239], v[36:37], v[52:53], v[238:239]
	global_store_dwordx4 v[202:203], v[232:235], off offset:512
	global_store_dwordx4 v[202:203], v[236:239], off offset:528
	s_nop 1
	global_load_dwordx4 v[232:235], v[200:201], off offset:512
	global_load_dwordx4 v[236:239], v[200:201], off offset:528
	s_waitcnt vmcnt(12)
	v_pk_fma_f32 v[208:209], v[30:31], v[78:79], v[208:209]
	v_pk_fma_f32 v[210:211], v[32:33], v[80:81], v[210:211]
	v_pk_fma_f32 v[212:213], v[26:27], v[74:75], v[212:213]
	v_pk_fma_f32 v[214:215], v[28:29], v[76:77], v[214:215]
	s_mov_b64 s[98:99], 0xa0000
	v_lshl_add_u64 v[202:203], v[156:157], 0, s[98:99]
	global_store_dwordx4 v[202:203], v[208:211], off
	global_store_dwordx4 v[202:203], v[212:215], off offset:16
	s_waitcnt vmcnt(10)
	v_pk_fma_f32 v[216:217], v[22:23], v[54:55], v[216:217]
	v_pk_fma_f32 v[218:219], v[24:25], v[56:57], v[218:219]
	v_pk_fma_f32 v[220:221], v[18:19], v[50:51], v[220:221]
	v_pk_fma_f32 v[222:223], v[20:21], v[52:53], v[222:223]
	global_store_dwordx4 v[202:203], v[216:219], off offset:512
	global_store_dwordx4 v[202:203], v[220:223], off offset:528
	s_waitcnt vmcnt(8)
	v_pk_fma_f32 v[224:225], v[14:15], v[78:79], v[224:225]
	v_pk_fma_f32 v[226:227], v[16:17], v[80:81], v[226:227]
	v_pk_fma_f32 v[228:229], v[10:11], v[74:75], v[228:229]
	v_pk_fma_f32 v[230:231], v[12:13], v[76:77], v[230:231]
	s_mov_b64 s[98:99], 0xb0000
	v_lshl_add_u64 v[202:203], v[156:157], 0, s[98:99]
	global_store_dwordx4 v[202:203], v[224:227], off
	global_store_dwordx4 v[202:203], v[228:231], off offset:16
	s_waitcnt vmcnt(6)
	v_pk_fma_f32 v[232:233], v[6:7], v[54:55], v[232:233]
	v_pk_fma_f32 v[234:235], v[8:9], v[56:57], v[234:235]
	v_pk_fma_f32 v[236:237], v[2:3], v[50:51], v[236:237]
	v_pk_fma_f32 v[238:239], v[4:5], v[52:53], v[238:239]
	global_store_dwordx4 v[202:203], v[232:235], off offset:512
	global_store_dwordx4 v[202:203], v[236:239], off offset:528
	s_mov_b32 s7, 0xb0000
	s_mov_b64 s[16:17], -1
	s_andn2_b64 vcc, exec, s[0:1]
	s_cbranch_vccnz .LBB0_804
	s_andn2_b64 vcc, exec, s[2:3]
	s_cbranch_vccnz .LBB0_803
	s_barrier
	s_branch .LBB0_803

; __global__ void __launch_bounds__(512, 2) fwd_mega(Args a) {
	.amdhsa_kernel _Z8fwd_mega4Args
		.amdhsa_group_segment_fixed_size 0
		.amdhsa_private_segment_fixed_size 0
		.amdhsa_kernarg_size 424
		.amdhsa_user_sgpr_count 2
		.amdhsa_user_sgpr_dispatch_ptr 0
		.amdhsa_user_sgpr_queue_ptr 0
		.amdhsa_user_sgpr_kernarg_segment_ptr 1
		.amdhsa_user_sgpr_dispatch_id 0
		.amdhsa_user_sgpr_kernarg_preload_length 0
		.amdhsa_user_sgpr_kernarg_preload_offset 0
		.amdhsa_user_sgpr_private_segment_size 0
		.amdhsa_uses_dynamic_stack 0
		.amdhsa_enable_private_segment 0
		.amdhsa_system_sgpr_workgroup_id_x 1
		.amdhsa_system_sgpr_workgroup_id_y 0
		.amdhsa_system_sgpr_workgroup_id_z 0
		.amdhsa_system_sgpr_workgroup_info 0
		.amdhsa_system_vgpr_workitem_id 2
		.amdhsa_next_free_vgpr 256
		.amdhsa_next_free_sgpr 100
		.amdhsa_accum_offset 256
		.amdhsa_reserve_vcc 1
		.amdhsa_float_round_mode_32 0
		.amdhsa_float_round_mode_16_64 0
		.amdhsa_float_denorm_mode_32 3
		.amdhsa_float_denorm_mode_16_64 3
		.amdhsa_dx10_clamp 1
		.amdhsa_ieee_mode 1
		.amdhsa_fp16_overflow 0
		.amdhsa_tg_split 0
		.amdhsa_exception_fp_ieee_invalid_op 0
		.amdhsa_exception_fp_denorm_src 0
		.amdhsa_exception_fp_ieee_div_zero 0
		.amdhsa_exception_fp_ieee_overflow 0
		.amdhsa_exception_fp_ieee_underflow 0
		.amdhsa_exception_fp_ieee_inexact 0
		.amdhsa_exception_int_div_zero 0
	.end_amdhsa_kernel

; __global__ void __launch_bounds__(512, 2) fwd_mega(Args a) {
amdhsa.kernels:
  - .agpr_count:     0
    .args:
      - .offset:         0
        .size:           168
        .value_kind:     by_value
      - .offset:         168
        .size:           4
        .value_kind:     hidden_block_count_x
      - .offset:         172
        .size:           4
        .value_kind:     hidden_block_count_y
      - .offset:         176
        .size:           4
        .value_kind:     hidden_block_count_z
      - .offset:         180
        .size:           2
        .value_kind:     hidden_group_size_x
      - .offset:         182
        .size:           2
        .value_kind:     hidden_group_size_y
      - .offset:         184
        .size:           2
        .value_kind:     hidden_group_size_z
      - .offset:         186
        .size:           2
        .value_kind:     hidden_remainder_x
      - .offset:         188
        .size:           2
        .value_kind:     hidden_remainder_y
      - .offset:         190
        .size:           2
        .value_kind:     hidden_remainder_z
      - .offset:         208
        .size:           8
        .value_kind:     hidden_global_offset_x
      - .offset:         216
        .size:           8
        .value_kind:     hidden_global_offset_y
      - .offset:         224
        .size:           8
        .value_kind:     hidden_global_offset_z
      - .offset:         232
        .size:           2
        .value_kind:     hidden_grid_dims
      - .offset:         256
        .size:           8
        .value_kind:     hidden_multigrid_sync_arg
      - .offset:         288
        .size:           4
        .value_kind:     hidden_dynamic_lds_size
    .group_segment_fixed_size: 0
    .kernarg_segment_align: 8
    .kernarg_segment_size: 424
    .language:       OpenCL C
    .language_version:
      - 2
      - 0
    .max_flat_workgroup_size: 512
    .name:           _Z8fwd_mega4Args
    .private_segment_fixed_size: 0
    .sgpr_count:     106
    .sgpr_spill_count: 287
    .symbol:         _Z8fwd_mega4Args.kd
    .uniform_work_group_size: 1
    .uses_dynamic_stack: false
    .vgpr_count:     256
    .vgpr_spill_count: 0
    .wavefront_size: 64
